# m32 + index emit pass: the mask-word address and the 4-bit shift are per-lane constants plus 16 bytes per tile, so they are computed once per unit (pre-shifted select constants, ds_or offset immediate
# speedup vs baseline: 1.0069x; 1.0022x over previous
.LBB0_2327:
	v_add_u32_e32 v2, 0, v4
	v_add_u32_e32 v2, 0x22000, v2
	ds_read2_b32 v[6:7], v2 offset1:2
	s_add_i32 s0, 0, 0x20000
	v_lshl_add_u32 v4, v167, 9, s0
	v_and_b32_e32 v207, 28, v41
	v_ashrrev_i32_e32 v203, 5, v41
	v_lshlrev_b32_e64 v204, v207, 1
	v_lshlrev_b32_e64 v205, v207, 2
	v_lshlrev_b32_e64 v206, v207, 4
	v_lshlrev_b32_e64 v207, v207, 8
	v_lshl_add_u32 v203, v203, 2, v4
	s_mov_b32 s0, 0x3fffff
	s_waitcnt lgkmcnt(0)
	v_lshlrev_b32_e32 v3, 10, v6
	v_add_u32_e32 v2, 0x400, v3
	v_cmp_ne_u32_e32 vcc, s0, v6
	v_cmp_ne_u32_e64 s[40:41], 0, v7
	v_readlane_b32 s0, v251, 33
	v_cndmask_b32_e32 v2, -1, v2, vcc
	v_cndmask_b32_e64 v5, 1, v2, s[40:41]
	s_and_b64 vcc, exec, s[28:29]
	v_lshl_add_u32 v2, v167, 2, s0
	s_cbranch_vccnz .LBB0_2344
	v_cmp_ge_u32_e32 vcc, v171, v5
	s_nop 1
	v_cndmask_b32_e64 v6, 0, v204, vcc
	v_cmp_lt_u32_e32 vcc, v170, v5
	s_nop 1
	v_cndmask_b32_e64 v7, v205, 0, vcc
	v_cmp_lt_u32_e32 vcc, v169, v5
	v_or_b32_e32 v6, v7, v6
	s_nop 0
	v_cndmask_b32_e64 v7, v206, 0, vcc
	v_cmp_lt_u32_e32 vcc, v168, v5
	s_nop 1
	v_cndmask_b32_e64 v8, v207, 0, vcc
	v_or3_b32 v6, v6, v7, v8
	v_cmp_ne_u32_e32 vcc, 0, v6
	s_and_saveexec_b64 s[0:1], vcc
	ds_or_b32 v203, v6
	s_or_b64 exec, exec, s[0:1]
	v_xor_b32_e32 v7, v3, v169
	v_xor_b32_e32 v6, v3, v168
	v_xor_b32_e32 v9, v3, v171
	v_xor_b32_e32 v8, v3, v170
	v_min_u32_e32 v10, v7, v6
	v_min3_u32 v10, v9, v8, v10
	v_cmp_gt_u32_e32 vcc, s27, v10
	s_and_b64 s[8:9], s[40:41], vcc
	s_and_saveexec_b64 s[0:1], s[8:9]
	s_cbranch_execz .LBB0_2343
	v_cmp_gt_u32_e32 vcc, s27, v9
	s_and_saveexec_b64 s[8:9], vcc
	s_cbranch_execz .LBB0_2334
	ds_add_rtn_u32 v9, v2, v186
	s_waitcnt lgkmcnt(0)
	v_cmp_gt_u32_e32 vcc, 64, v9
	s_and_b64 exec, exec, vcc
	v_lshlrev_b32_e32 v10, 12, v171
	s_mov_b32 s7, 0x3ff000
	v_lshl_add_u32 v9, v9, 2, v40
	v_and_or_b32 v10, v10, s7, v41
	ds_write_b32 v9, v10

.LBB0_2344:
	s_cmp_lt_i32 s77, 8
	s_cbranch_scc1 .LBB0_2600
	v_cmp_ge_u32_e32 vcc, v166, v5
	v_add_u32_e32 v6, 0x80, v41
	s_nop 0
	v_cndmask_b32_e64 v7, 0, v204, vcc
	v_cmp_lt_u32_e32 vcc, v165, v5
	s_nop 1
	v_cndmask_b32_e64 v8, v205, 0, vcc
	v_cmp_lt_u32_e32 vcc, v164, v5
	v_or_b32_e32 v7, v8, v7
	s_nop 0
	v_cndmask_b32_e64 v8, v206, 0, vcc
	v_cmp_lt_u32_e32 vcc, v163, v5
	s_nop 1
	v_cndmask_b32_e64 v9, v207, 0, vcc
	v_or3_b32 v7, v7, v8, v9
	v_cmp_ne_u32_e32 vcc, 0, v7
	s_and_saveexec_b64 s[0:1], vcc
	ds_or_b32 v203, v7 offset:16
	s_or_b64 exec, exec, s[0:1]
	v_xor_b32_e32 v8, v3, v164
	v_xor_b32_e32 v7, v3, v163
	v_xor_b32_e32 v10, v3, v166
	v_xor_b32_e32 v9, v3, v165
	v_min_u32_e32 v11, v8, v7
	v_min3_u32 v11, v10, v9, v11
	v_cmp_gt_u32_e32 vcc, s27, v11
	s_and_b64 s[8:9], s[40:41], vcc
	s_and_saveexec_b64 s[0:1], s[8:9]
	s_cbranch_execz .LBB0_2360
	v_cmp_gt_u32_e32 vcc, s27, v10
	s_and_saveexec_b64 s[8:9], vcc
	s_cbranch_execz .LBB0_2351
	ds_add_rtn_u32 v10, v2, v186
	s_waitcnt lgkmcnt(0)
	v_cmp_gt_u32_e32 vcc, 64, v10
	s_and_b64 exec, exec, vcc
	v_lshlrev_b32_e32 v11, 12, v166
	s_mov_b32 s7, 0x3ff000
	v_lshl_add_u32 v10, v10, 2, v40
	v_and_or_b32 v11, v11, s7, v6
	ds_write_b32 v10, v11

.LBB0_2362:
	v_cmp_ge_u32_e32 vcc, v158, v5
	v_add_u32_e32 v6, 0x180, v41
	s_nop 0
	v_cndmask_b32_e64 v7, 0, v204, vcc
	v_cmp_lt_u32_e32 vcc, v157, v5
	s_nop 1
	v_cndmask_b32_e64 v8, v205, 0, vcc
	v_cmp_lt_u32_e32 vcc, v156, v5
	v_or_b32_e32 v7, v8, v7
	s_nop 0
	v_cndmask_b32_e64 v8, v206, 0, vcc
	v_cmp_lt_u32_e32 vcc, v155, v5
	s_nop 1
	v_cndmask_b32_e64 v9, v207, 0, vcc
	v_or3_b32 v7, v7, v8, v9
	v_cmp_ne_u32_e32 vcc, 0, v7
	s_and_saveexec_b64 s[0:1], vcc
	ds_or_b32 v203, v7 offset:48
	s_or_b64 exec, exec, s[0:1]
	v_xor_b32_e32 v8, v3, v156
	v_xor_b32_e32 v7, v3, v155
	v_xor_b32_e32 v10, v3, v158
	v_xor_b32_e32 v9, v3, v157
	v_min_u32_e32 v11, v8, v7
	v_min3_u32 v11, v10, v9, v11
	v_cmp_gt_u32_e32 vcc, s27, v11
	s_and_b64 s[8:9], s[40:41], vcc
	s_and_saveexec_b64 s[0:1], s[8:9]
	s_cbranch_execz .LBB0_2377
	v_cmp_gt_u32_e32 vcc, s27, v10
	s_and_saveexec_b64 s[8:9], vcc
	s_cbranch_execz .LBB0_2368
	ds_add_rtn_u32 v10, v2, v186
	s_waitcnt lgkmcnt(0)
	v_cmp_gt_u32_e32 vcc, 64, v10
	s_and_b64 exec, exec, vcc
	v_lshlrev_b32_e32 v11, 12, v158
	s_mov_b32 s7, 0x3ff000
	v_lshl_add_u32 v10, v10, 2, v40
	v_and_or_b32 v11, v11, s7, v6
	ds_write_b32 v10, v11

.LBB0_2379:
	v_cmp_ge_u32_e32 vcc, v150, v5
	v_add_u32_e32 v6, 0x280, v41
	s_nop 0
	v_cndmask_b32_e64 v7, 0, v204, vcc
	v_cmp_lt_u32_e32 vcc, v149, v5
	s_nop 1
	v_cndmask_b32_e64 v8, v205, 0, vcc
	v_cmp_lt_u32_e32 vcc, v148, v5
	v_or_b32_e32 v7, v8, v7
	s_nop 0
	v_cndmask_b32_e64 v8, v206, 0, vcc
	v_cmp_lt_u32_e32 vcc, v147, v5
	s_nop 1
	v_cndmask_b32_e64 v9, v207, 0, vcc
	v_or3_b32 v7, v7, v8, v9
	v_cmp_ne_u32_e32 vcc, 0, v7
	s_and_saveexec_b64 s[0:1], vcc
	ds_or_b32 v203, v7 offset:80
	s_or_b64 exec, exec, s[0:1]
	v_xor_b32_e32 v8, v3, v148
	v_xor_b32_e32 v7, v3, v147
	v_xor_b32_e32 v10, v3, v150
	v_xor_b32_e32 v9, v3, v149
	v_min_u32_e32 v11, v8, v7
	v_min3_u32 v11, v10, v9, v11
	v_cmp_gt_u32_e32 vcc, s27, v11
	s_and_b64 s[8:9], s[40:41], vcc
	s_and_saveexec_b64 s[0:1], s[8:9]
	s_cbranch_execz .LBB0_2394
	v_cmp_gt_u32_e32 vcc, s27, v10
	s_and_saveexec_b64 s[8:9], vcc
	s_cbranch_execz .LBB0_2385
	ds_add_rtn_u32 v10, v2, v186
	s_waitcnt lgkmcnt(0)
	v_cmp_gt_u32_e32 vcc, 64, v10
	s_and_b64 exec, exec, vcc
	v_lshlrev_b32_e32 v11, 12, v150
	s_mov_b32 s7, 0x3ff000
	v_lshl_add_u32 v10, v10, 2, v40
	v_and_or_b32 v11, v11, s7, v6
	ds_write_b32 v10, v11

.LBB0_2396:
	v_cmp_ge_u32_e32 vcc, v142, v5
	v_add_u32_e32 v6, 0x380, v41
	s_nop 0
	v_cndmask_b32_e64 v7, 0, v204, vcc
	v_cmp_lt_u32_e32 vcc, v141, v5
	s_nop 1
	v_cndmask_b32_e64 v8, v205, 0, vcc
	v_cmp_lt_u32_e32 vcc, v140, v5
	v_or_b32_e32 v7, v8, v7
	s_nop 0
	v_cndmask_b32_e64 v8, v206, 0, vcc
	v_cmp_lt_u32_e32 vcc, v139, v5
	s_nop 1
	v_cndmask_b32_e64 v9, v207, 0, vcc
	v_or3_b32 v7, v7, v8, v9
	v_cmp_ne_u32_e32 vcc, 0, v7
	s_and_saveexec_b64 s[0:1], vcc
	ds_or_b32 v203, v7 offset:112
	s_or_b64 exec, exec, s[0:1]
	v_xor_b32_e32 v8, v3, v140
	v_xor_b32_e32 v7, v3, v139
	v_xor_b32_e32 v10, v3, v142
	v_xor_b32_e32 v9, v3, v141
	v_min_u32_e32 v11, v8, v7
	v_min3_u32 v11, v10, v9, v11
	v_cmp_gt_u32_e32 vcc, s27, v11
	s_and_b64 s[8:9], s[40:41], vcc
	s_and_saveexec_b64 s[0:1], s[8:9]
	s_cbranch_execz .LBB0_2411
	v_cmp_gt_u32_e32 vcc, s27, v10
	s_and_saveexec_b64 s[8:9], vcc
	s_cbranch_execz .LBB0_2402
	ds_add_rtn_u32 v10, v2, v186
	s_waitcnt lgkmcnt(0)
	v_cmp_gt_u32_e32 vcc, 64, v10
	s_and_b64 exec, exec, vcc
	v_lshlrev_b32_e32 v11, 12, v142
	s_mov_b32 s7, 0x3ff000
	v_lshl_add_u32 v10, v10, 2, v40
	v_and_or_b32 v11, v11, s7, v6
	ds_write_b32 v10, v11

.LBB0_2413:
	v_cmp_ge_u32_e32 vcc, v134, v5
	v_add_u32_e32 v6, 0x480, v41
	s_nop 0
	v_cndmask_b32_e64 v7, 0, v204, vcc
	v_cmp_lt_u32_e32 vcc, v133, v5
	s_nop 1
	v_cndmask_b32_e64 v8, v205, 0, vcc
	v_cmp_lt_u32_e32 vcc, v132, v5
	v_or_b32_e32 v7, v8, v7
	s_nop 0
	v_cndmask_b32_e64 v8, v206, 0, vcc
	v_cmp_lt_u32_e32 vcc, v131, v5
	s_nop 1
	v_cndmask_b32_e64 v9, v207, 0, vcc
	v_or3_b32 v7, v7, v8, v9
	v_cmp_ne_u32_e32 vcc, 0, v7
	s_and_saveexec_b64 s[0:1], vcc
	ds_or_b32 v203, v7 offset:144
	s_or_b64 exec, exec, s[0:1]
	v_xor_b32_e32 v8, v3, v132
	v_xor_b32_e32 v7, v3, v131
	v_xor_b32_e32 v10, v3, v134
	v_xor_b32_e32 v9, v3, v133
	v_min_u32_e32 v11, v8, v7
	v_min3_u32 v11, v10, v9, v11
	v_cmp_gt_u32_e32 vcc, s27, v11
	s_and_b64 s[8:9], s[40:41], vcc
	s_and_saveexec_b64 s[0:1], s[8:9]
	s_cbranch_execz .LBB0_2428
	v_cmp_gt_u32_e32 vcc, s27, v10
	s_and_saveexec_b64 s[8:9], vcc
	s_cbranch_execz .LBB0_2419
	ds_add_rtn_u32 v10, v2, v186
	s_waitcnt lgkmcnt(0)
	v_cmp_gt_u32_e32 vcc, 64, v10
	s_and_b64 exec, exec, vcc
	v_lshlrev_b32_e32 v11, 12, v134
	s_mov_b32 s7, 0x3ff000
	v_lshl_add_u32 v10, v10, 2, v40
	v_and_or_b32 v11, v11, s7, v6
	ds_write_b32 v10, v11

.LBB0_2430:
	v_cmp_ge_u32_e32 vcc, v126, v5
	v_add_u32_e32 v6, 0x580, v41
	s_nop 0
	v_cndmask_b32_e64 v7, 0, v204, vcc
	v_cmp_lt_u32_e32 vcc, v125, v5
	s_nop 1
	v_cndmask_b32_e64 v8, v205, 0, vcc
	v_cmp_lt_u32_e32 vcc, v124, v5
	v_or_b32_e32 v7, v8, v7
	s_nop 0
	v_cndmask_b32_e64 v8, v206, 0, vcc
	v_cmp_lt_u32_e32 vcc, v123, v5
	s_nop 1
	v_cndmask_b32_e64 v9, v207, 0, vcc
	v_or3_b32 v7, v7, v8, v9
	v_cmp_ne_u32_e32 vcc, 0, v7
	s_and_saveexec_b64 s[0:1], vcc
	ds_or_b32 v203, v7 offset:176
	s_or_b64 exec, exec, s[0:1]
	v_xor_b32_e32 v8, v3, v124
	v_xor_b32_e32 v7, v3, v123
	v_xor_b32_e32 v10, v3, v126
	v_xor_b32_e32 v9, v3, v125
	v_min_u32_e32 v11, v8, v7
	v_min3_u32 v11, v10, v9, v11
	v_cmp_gt_u32_e32 vcc, s27, v11
	s_and_b64 s[8:9], s[40:41], vcc
	s_and_saveexec_b64 s[0:1], s[8:9]
	s_cbranch_execz .LBB0_2445
	v_cmp_gt_u32_e32 vcc, s27, v10
	s_and_saveexec_b64 s[8:9], vcc
	s_cbranch_execz .LBB0_2436
	ds_add_rtn_u32 v10, v2, v186
	s_waitcnt lgkmcnt(0)
	v_cmp_gt_u32_e32 vcc, 64, v10
	s_and_b64 exec, exec, vcc
	v_lshlrev_b32_e32 v11, 12, v126
	s_mov_b32 s7, 0x3ff000
	v_lshl_add_u32 v10, v10, 2, v40
	v_and_or_b32 v11, v11, s7, v6
	ds_write_b32 v10, v11

.LBB0_2447:
	v_cmp_ge_u32_e32 vcc, v118, v5
	v_add_u32_e32 v6, 0x680, v41
	s_nop 0
	v_cndmask_b32_e64 v7, 0, v204, vcc
	v_cmp_lt_u32_e32 vcc, v117, v5
	s_nop 1
	v_cndmask_b32_e64 v8, v205, 0, vcc
	v_cmp_lt_u32_e32 vcc, v115, v5
	v_or_b32_e32 v7, v8, v7
	s_nop 0
	v_cndmask_b32_e64 v8, v206, 0, vcc
	v_cmp_lt_u32_e32 vcc, v114, v5
	s_nop 1
	v_cndmask_b32_e64 v9, v207, 0, vcc
	v_or3_b32 v7, v7, v8, v9
	v_cmp_ne_u32_e32 vcc, 0, v7
	s_and_saveexec_b64 s[0:1], vcc
	ds_or_b32 v203, v7 offset:208
	s_or_b64 exec, exec, s[0:1]
	v_xor_b32_e32 v8, v3, v115
	v_xor_b32_e32 v7, v3, v114
	v_xor_b32_e32 v10, v3, v118
	v_xor_b32_e32 v9, v3, v117
	v_min_u32_e32 v11, v8, v7
	v_min3_u32 v11, v10, v9, v11
	v_cmp_gt_u32_e32 vcc, s27, v11
	s_and_b64 s[8:9], s[40:41], vcc
	s_and_saveexec_b64 s[0:1], s[8:9]
	s_cbranch_execz .LBB0_2462
	v_cmp_gt_u32_e32 vcc, s27, v10
	s_and_saveexec_b64 s[8:9], vcc
	s_cbranch_execz .LBB0_2453
	ds_add_rtn_u32 v10, v2, v186
	s_waitcnt lgkmcnt(0)
	v_cmp_gt_u32_e32 vcc, 64, v10
	s_and_b64 exec, exec, vcc
	v_lshlrev_b32_e32 v11, 12, v118
	s_mov_b32 s7, 0x3ff000
	v_lshl_add_u32 v10, v10, 2, v40
	v_and_or_b32 v11, v11, s7, v6
	ds_write_b32 v10, v11

.LBB0_2464:
	v_cmp_ge_u32_e32 vcc, v109, v5
	v_add_u32_e32 v6, 0x780, v41
	s_nop 0
	v_cndmask_b32_e64 v7, 0, v204, vcc
	v_cmp_lt_u32_e32 vcc, v108, v5
	s_nop 1
	v_cndmask_b32_e64 v8, v205, 0, vcc
	v_cmp_lt_u32_e32 vcc, v107, v5
	v_or_b32_e32 v7, v8, v7
	s_nop 0
	v_cndmask_b32_e64 v8, v206, 0, vcc
	v_cmp_lt_u32_e32 vcc, v105, v5
	s_nop 1
	v_cndmask_b32_e64 v9, v207, 0, vcc
	v_or3_b32 v7, v7, v8, v9
	v_cmp_ne_u32_e32 vcc, 0, v7
	s_and_saveexec_b64 s[0:1], vcc
	ds_or_b32 v203, v7 offset:240
	s_or_b64 exec, exec, s[0:1]
	v_xor_b32_e32 v8, v3, v107
	v_xor_b32_e32 v7, v3, v105
	v_xor_b32_e32 v10, v3, v109
	v_xor_b32_e32 v9, v3, v108
	v_min_u32_e32 v11, v8, v7
	v_min3_u32 v11, v10, v9, v11
	v_cmp_gt_u32_e32 vcc, s27, v11
	s_and_b64 s[8:9], s[40:41], vcc
	s_and_saveexec_b64 s[0:1], s[8:9]
	s_cbranch_execz .LBB0_2479
	v_cmp_gt_u32_e32 vcc, s27, v10
	s_and_saveexec_b64 s[8:9], vcc
	s_cbranch_execz .LBB0_2470
	ds_add_rtn_u32 v10, v2, v186
	s_waitcnt lgkmcnt(0)
	v_cmp_gt_u32_e32 vcc, 64, v10
	s_and_b64 exec, exec, vcc
	v_lshlrev_b32_e32 v11, 12, v109
	s_mov_b32 s7, 0x3ff000
	v_lshl_add_u32 v10, v10, 2, v40
	v_and_or_b32 v11, v11, s7, v6
	ds_write_b32 v10, v11

.LBB0_2481:
	v_cmp_ge_u32_e32 vcc, v101, v5
	v_add_u32_e32 v6, 0x880, v41
	s_nop 0
	v_cndmask_b32_e64 v7, 0, v204, vcc
	v_cmp_lt_u32_e32 vcc, v100, v5
	s_nop 1
	v_cndmask_b32_e64 v8, v205, 0, vcc
	v_cmp_lt_u32_e32 vcc, v99, v5
	v_or_b32_e32 v7, v8, v7
	s_nop 0
	v_cndmask_b32_e64 v8, v206, 0, vcc
	v_cmp_lt_u32_e32 vcc, v98, v5
	s_nop 1
	v_cndmask_b32_e64 v9, v207, 0, vcc
	v_or3_b32 v7, v7, v8, v9
	v_cmp_ne_u32_e32 vcc, 0, v7
	s_and_saveexec_b64 s[0:1], vcc
	ds_or_b32 v203, v7 offset:272
	s_or_b64 exec, exec, s[0:1]
	v_xor_b32_e32 v8, v3, v99
	v_xor_b32_e32 v7, v3, v98
	v_xor_b32_e32 v10, v3, v101
	v_xor_b32_e32 v9, v3, v100
	v_min_u32_e32 v11, v8, v7
	v_min3_u32 v11, v10, v9, v11
	v_cmp_gt_u32_e32 vcc, s27, v11
	s_and_b64 s[8:9], s[40:41], vcc
	s_and_saveexec_b64 s[0:1], s[8:9]
	s_cbranch_execz .LBB0_2496
	v_cmp_gt_u32_e32 vcc, s27, v10
	s_and_saveexec_b64 s[8:9], vcc
	s_cbranch_execz .LBB0_2487
	ds_add_rtn_u32 v10, v2, v186
	s_waitcnt lgkmcnt(0)
	v_cmp_gt_u32_e32 vcc, 64, v10
	s_and_b64 exec, exec, vcc
	v_lshlrev_b32_e32 v11, 12, v101
	s_mov_b32 s7, 0x3ff000
	v_lshl_add_u32 v10, v10, 2, v40
	v_and_or_b32 v11, v11, s7, v6
	ds_write_b32 v10, v11

.LBB0_2498:
	v_cmp_ge_u32_e32 vcc, v93, v5
	v_add_u32_e32 v6, 0x980, v41
	s_nop 0
	v_cndmask_b32_e64 v7, 0, v204, vcc
	v_cmp_lt_u32_e32 vcc, v92, v5
	s_nop 1
	v_cndmask_b32_e64 v8, v205, 0, vcc
	v_cmp_lt_u32_e32 vcc, v91, v5
	v_or_b32_e32 v7, v8, v7
	s_nop 0
	v_cndmask_b32_e64 v8, v206, 0, vcc
	v_cmp_lt_u32_e32 vcc, v90, v5
	s_nop 1
	v_cndmask_b32_e64 v9, v207, 0, vcc
	v_or3_b32 v7, v7, v8, v9
	v_cmp_ne_u32_e32 vcc, 0, v7
	s_and_saveexec_b64 s[0:1], vcc
	ds_or_b32 v203, v7 offset:304
	s_or_b64 exec, exec, s[0:1]
	v_xor_b32_e32 v8, v3, v91
	v_xor_b32_e32 v7, v3, v90
	v_xor_b32_e32 v10, v3, v93
	v_xor_b32_e32 v9, v3, v92
	v_min_u32_e32 v11, v8, v7
	v_min3_u32 v11, v10, v9, v11
	v_cmp_gt_u32_e32 vcc, s27, v11
	s_and_b64 s[8:9], s[40:41], vcc
	s_and_saveexec_b64 s[0:1], s[8:9]
	s_cbranch_execz .LBB0_2513
	v_cmp_gt_u32_e32 vcc, s27, v10
	s_and_saveexec_b64 s[8:9], vcc
	s_cbranch_execz .LBB0_2504
	ds_add_rtn_u32 v10, v2, v186
	s_waitcnt lgkmcnt(0)
	v_cmp_gt_u32_e32 vcc, 64, v10
	s_and_b64 exec, exec, vcc
	v_lshlrev_b32_e32 v11, 12, v93
	s_mov_b32 s7, 0x3ff000
	v_lshl_add_u32 v10, v10, 2, v40
	v_and_or_b32 v11, v11, s7, v6
	ds_write_b32 v10, v11

.LBB0_2515:
	v_cmp_ge_u32_e32 vcc, v85, v5
	v_add_u32_e32 v6, 0xa80, v41
	s_nop 0
	v_cndmask_b32_e64 v7, 0, v204, vcc
	v_cmp_lt_u32_e32 vcc, v84, v5
	s_nop 1
	v_cndmask_b32_e64 v8, v205, 0, vcc
	v_cmp_lt_u32_e32 vcc, v83, v5
	v_or_b32_e32 v7, v8, v7
	s_nop 0
	v_cndmask_b32_e64 v8, v206, 0, vcc
	v_cmp_lt_u32_e32 vcc, v82, v5
	s_nop 1
	v_cndmask_b32_e64 v9, v207, 0, vcc
	v_or3_b32 v7, v7, v8, v9
	v_cmp_ne_u32_e32 vcc, 0, v7
	s_and_saveexec_b64 s[0:1], vcc
	ds_or_b32 v203, v7 offset:336
	s_or_b64 exec, exec, s[0:1]
	v_xor_b32_e32 v8, v3, v83
	v_xor_b32_e32 v7, v3, v82
	v_xor_b32_e32 v10, v3, v85
	v_xor_b32_e32 v9, v3, v84
	v_min_u32_e32 v11, v8, v7
	v_min3_u32 v11, v10, v9, v11
	v_cmp_gt_u32_e32 vcc, s27, v11
	s_and_b64 s[8:9], s[40:41], vcc
	s_and_saveexec_b64 s[0:1], s[8:9]
	s_cbranch_execz .LBB0_2530
	v_cmp_gt_u32_e32 vcc, s27, v10
	s_and_saveexec_b64 s[8:9], vcc
	s_cbranch_execz .LBB0_2521
	ds_add_rtn_u32 v10, v2, v186
	s_waitcnt lgkmcnt(0)
	v_cmp_gt_u32_e32 vcc, 64, v10
	s_and_b64 exec, exec, vcc
	v_lshlrev_b32_e32 v11, 12, v85
	s_mov_b32 s7, 0x3ff000
	v_lshl_add_u32 v10, v10, 2, v40
	v_and_or_b32 v11, v11, s7, v6
	ds_write_b32 v10, v11

.LBB0_2532:
	v_cmp_ge_u32_e32 vcc, v77, v5
	v_add_u32_e32 v6, 0xb80, v41
	s_nop 0
	v_cndmask_b32_e64 v7, 0, v204, vcc
	v_cmp_lt_u32_e32 vcc, v76, v5
	s_nop 1
	v_cndmask_b32_e64 v8, v205, 0, vcc
	v_cmp_lt_u32_e32 vcc, v75, v5
	v_or_b32_e32 v7, v8, v7
	s_nop 0
	v_cndmask_b32_e64 v8, v206, 0, vcc
	v_cmp_lt_u32_e32 vcc, v74, v5
	s_nop 1
	v_cndmask_b32_e64 v9, v207, 0, vcc
	v_or3_b32 v7, v7, v8, v9
	v_cmp_ne_u32_e32 vcc, 0, v7
	s_and_saveexec_b64 s[0:1], vcc
	ds_or_b32 v203, v7 offset:368
	s_or_b64 exec, exec, s[0:1]
	v_xor_b32_e32 v8, v3, v75
	v_xor_b32_e32 v7, v3, v74
	v_xor_b32_e32 v10, v3, v77
	v_xor_b32_e32 v9, v3, v76
	v_min_u32_e32 v11, v8, v7
	v_min3_u32 v11, v10, v9, v11
	v_cmp_gt_u32_e32 vcc, s27, v11
	s_and_b64 s[8:9], s[40:41], vcc
	s_and_saveexec_b64 s[0:1], s[8:9]
	s_cbranch_execz .LBB0_2547
	v_cmp_gt_u32_e32 vcc, s27, v10
	s_and_saveexec_b64 s[8:9], vcc
	s_cbranch_execz .LBB0_2538
	ds_add_rtn_u32 v10, v2, v186
	s_waitcnt lgkmcnt(0)
	v_cmp_gt_u32_e32 vcc, 64, v10
	s_and_b64 exec, exec, vcc
	v_lshlrev_b32_e32 v11, 12, v77
	s_mov_b32 s7, 0x3ff000
	v_lshl_add_u32 v10, v10, 2, v40
	v_and_or_b32 v11, v11, s7, v6
	ds_write_b32 v10, v11

.LBB0_2549:
	v_cmp_ge_u32_e32 vcc, v69, v5
	v_add_u32_e32 v6, 0xc80, v41
	s_nop 0
	v_cndmask_b32_e64 v7, 0, v204, vcc
	v_cmp_lt_u32_e32 vcc, v68, v5
	s_nop 1
	v_cndmask_b32_e64 v8, v205, 0, vcc
	v_cmp_lt_u32_e32 vcc, v67, v5
	v_or_b32_e32 v7, v8, v7
	s_nop 0
	v_cndmask_b32_e64 v8, v206, 0, vcc
	v_cmp_lt_u32_e32 vcc, v66, v5
	s_nop 1
	v_cndmask_b32_e64 v9, v207, 0, vcc
	v_or3_b32 v7, v7, v8, v9
	v_cmp_ne_u32_e32 vcc, 0, v7
	s_and_saveexec_b64 s[0:1], vcc
	ds_or_b32 v203, v7 offset:400
	s_or_b64 exec, exec, s[0:1]
	v_xor_b32_e32 v8, v3, v67
	v_xor_b32_e32 v7, v3, v66
	v_xor_b32_e32 v10, v3, v69
	v_xor_b32_e32 v9, v3, v68
	v_min_u32_e32 v11, v8, v7
	v_min3_u32 v11, v10, v9, v11
	v_cmp_gt_u32_e32 vcc, s27, v11
	s_and_b64 s[8:9], s[40:41], vcc
	s_and_saveexec_b64 s[0:1], s[8:9]
	s_cbranch_execz .LBB0_2564
	v_cmp_gt_u32_e32 vcc, s27, v10
	s_and_saveexec_b64 s[8:9], vcc
	s_cbranch_execz .LBB0_2555
	ds_add_rtn_u32 v10, v2, v186
	s_waitcnt lgkmcnt(0)
	v_cmp_gt_u32_e32 vcc, 64, v10
	s_and_b64 exec, exec, vcc
	v_lshlrev_b32_e32 v11, 12, v69
	s_mov_b32 s7, 0x3ff000
	v_lshl_add_u32 v10, v10, 2, v40
	v_and_or_b32 v11, v11, s7, v6
	ds_write_b32 v10, v11

.LBB0_2566:
	v_cmp_ge_u32_e32 vcc, v61, v5
	v_add_u32_e32 v6, 0xd80, v41
	s_nop 0
	v_cndmask_b32_e64 v7, 0, v204, vcc
	v_cmp_lt_u32_e32 vcc, v60, v5
	s_nop 1
	v_cndmask_b32_e64 v8, v205, 0, vcc
	v_cmp_lt_u32_e32 vcc, v59, v5
	v_or_b32_e32 v7, v8, v7
	s_nop 0
	v_cndmask_b32_e64 v8, v206, 0, vcc
	v_cmp_lt_u32_e32 vcc, v58, v5
	s_nop 1
	v_cndmask_b32_e64 v9, v207, 0, vcc
	v_or3_b32 v7, v7, v8, v9
	v_cmp_ne_u32_e32 vcc, 0, v7
	s_and_saveexec_b64 s[0:1], vcc
	ds_or_b32 v203, v7 offset:432
	s_or_b64 exec, exec, s[0:1]
	v_xor_b32_e32 v8, v3, v59
	v_xor_b32_e32 v7, v3, v58
	v_xor_b32_e32 v10, v3, v61
	v_xor_b32_e32 v9, v3, v60
	v_min_u32_e32 v11, v8, v7
	v_min3_u32 v11, v10, v9, v11
	v_cmp_gt_u32_e32 vcc, s27, v11
	s_and_b64 s[8:9], s[40:41], vcc
	s_and_saveexec_b64 s[0:1], s[8:9]
	s_cbranch_execz .LBB0_2581
	v_cmp_gt_u32_e32 vcc, s27, v10
	s_and_saveexec_b64 s[8:9], vcc
	s_cbranch_execz .LBB0_2572
	ds_add_rtn_u32 v10, v2, v186
	s_waitcnt lgkmcnt(0)
	v_cmp_gt_u32_e32 vcc, 64, v10
	s_and_b64 exec, exec, vcc
	v_lshlrev_b32_e32 v11, 12, v61
	s_mov_b32 s7, 0x3ff000
	v_lshl_add_u32 v10, v10, 2, v40
	v_and_or_b32 v11, v11, s7, v6
	ds_write_b32 v10, v11

.LBB0_2583:
	v_cmp_ge_u32_e32 vcc, v53, v5
	v_add_u32_e32 v6, 0xe80, v41
	s_nop 0
	v_cndmask_b32_e64 v7, 0, v204, vcc
	v_cmp_lt_u32_e32 vcc, v52, v5
	s_nop 1
	v_cndmask_b32_e64 v8, v205, 0, vcc
	v_cmp_lt_u32_e32 vcc, v51, v5
	v_or_b32_e32 v7, v8, v7
	s_nop 0
	v_cndmask_b32_e64 v8, v206, 0, vcc
	v_cmp_lt_u32_e32 vcc, v50, v5
	s_nop 1
	v_cndmask_b32_e64 v9, v207, 0, vcc
	v_or3_b32 v7, v7, v8, v9
	v_cmp_ne_u32_e32 vcc, 0, v7
	s_and_saveexec_b64 s[0:1], vcc
	ds_or_b32 v203, v7 offset:464
	s_or_b64 exec, exec, s[0:1]
	v_xor_b32_e32 v8, v3, v51
	v_xor_b32_e32 v7, v3, v50
	v_xor_b32_e32 v10, v3, v53
	v_xor_b32_e32 v9, v3, v52
	v_min_u32_e32 v11, v8, v7
	v_min3_u32 v11, v10, v9, v11
	v_cmp_gt_u32_e32 vcc, s27, v11
	s_and_b64 s[8:9], s[40:41], vcc
	s_and_saveexec_b64 s[0:1], s[8:9]
	s_cbranch_execz .LBB0_2598
	v_cmp_gt_u32_e32 vcc, s27, v10
	s_and_saveexec_b64 s[8:9], vcc
	s_cbranch_execz .LBB0_2589
	ds_add_rtn_u32 v10, v2, v186
	s_waitcnt lgkmcnt(0)
	v_cmp_gt_u32_e32 vcc, 64, v10
	s_and_b64 exec, exec, vcc
	v_lshlrev_b32_e32 v11, 12, v53
	s_mov_b32 s7, 0x3ff000
	v_lshl_add_u32 v10, v10, 2, v40
	v_and_or_b32 v11, v11, s7, v6
	ds_write_b32 v10, v11

.LBB0_2601:
	v_cmp_ge_u32_e32 vcc, v162, v5
	v_add_u32_e32 v6, 0x100, v41
	s_nop 0
	v_cndmask_b32_e64 v7, 0, v204, vcc
	v_cmp_lt_u32_e32 vcc, v161, v5
	s_nop 1
	v_cndmask_b32_e64 v8, v205, 0, vcc
	v_cmp_lt_u32_e32 vcc, v160, v5
	v_or_b32_e32 v7, v8, v7
	s_nop 0
	v_cndmask_b32_e64 v8, v206, 0, vcc
	v_cmp_lt_u32_e32 vcc, v159, v5
	s_nop 1
	v_cndmask_b32_e64 v9, v207, 0, vcc
	v_or3_b32 v7, v7, v8, v9
	v_cmp_ne_u32_e32 vcc, 0, v7
	s_and_saveexec_b64 s[0:1], vcc
	ds_or_b32 v203, v7 offset:32
	s_or_b64 exec, exec, s[0:1]
	v_xor_b32_e32 v8, v3, v160
	v_xor_b32_e32 v7, v3, v159
	v_xor_b32_e32 v10, v3, v162
	v_xor_b32_e32 v9, v3, v161
	v_min_u32_e32 v11, v8, v7
	v_min3_u32 v11, v10, v9, v11
	v_cmp_gt_u32_e32 vcc, s27, v11
	s_and_b64 s[8:9], s[40:41], vcc
	s_and_saveexec_b64 s[0:1], s[8:9]
	s_cbranch_execz .LBB0_2616
	v_cmp_gt_u32_e32 vcc, s27, v10
	s_and_saveexec_b64 s[8:9], vcc
	s_cbranch_execz .LBB0_2607
	ds_add_rtn_u32 v10, v2, v186
	s_waitcnt lgkmcnt(0)
	v_cmp_gt_u32_e32 vcc, 64, v10
	s_and_b64 exec, exec, vcc
	v_lshlrev_b32_e32 v11, 12, v162
	s_mov_b32 s7, 0x3ff000
	v_lshl_add_u32 v10, v10, 2, v40
	v_and_or_b32 v11, v11, s7, v6
	ds_write_b32 v10, v11

.LBB0_2618:
	v_cmp_ge_u32_e32 vcc, v154, v5
	v_add_u32_e32 v6, 0x200, v41
	s_nop 0
	v_cndmask_b32_e64 v7, 0, v204, vcc
	v_cmp_lt_u32_e32 vcc, v153, v5
	s_nop 1
	v_cndmask_b32_e64 v8, v205, 0, vcc
	v_cmp_lt_u32_e32 vcc, v152, v5
	v_or_b32_e32 v7, v8, v7
	s_nop 0
	v_cndmask_b32_e64 v8, v206, 0, vcc
	v_cmp_lt_u32_e32 vcc, v151, v5
	s_nop 1
	v_cndmask_b32_e64 v9, v207, 0, vcc
	v_or3_b32 v7, v7, v8, v9
	v_cmp_ne_u32_e32 vcc, 0, v7
	s_and_saveexec_b64 s[0:1], vcc
	ds_or_b32 v203, v7 offset:64
	s_or_b64 exec, exec, s[0:1]
	v_xor_b32_e32 v8, v3, v152
	v_xor_b32_e32 v7, v3, v151
	v_xor_b32_e32 v10, v3, v154
	v_xor_b32_e32 v9, v3, v153
	v_min_u32_e32 v11, v8, v7
	v_min3_u32 v11, v10, v9, v11
	v_cmp_gt_u32_e32 vcc, s27, v11
	s_and_b64 s[8:9], s[40:41], vcc
	s_and_saveexec_b64 s[0:1], s[8:9]
	s_cbranch_execz .LBB0_2633
	v_cmp_gt_u32_e32 vcc, s27, v10
	s_and_saveexec_b64 s[8:9], vcc
	s_cbranch_execz .LBB0_2624
	ds_add_rtn_u32 v10, v2, v186
	s_waitcnt lgkmcnt(0)
	v_cmp_gt_u32_e32 vcc, 64, v10
	s_and_b64 exec, exec, vcc
	v_lshlrev_b32_e32 v11, 12, v154
	s_mov_b32 s7, 0x3ff000
	v_lshl_add_u32 v10, v10, 2, v40
	v_and_or_b32 v11, v11, s7, v6
	ds_write_b32 v10, v11

.LBB0_2635:
	v_cmp_ge_u32_e32 vcc, v146, v5
	v_add_u32_e32 v6, 0x300, v41
	s_nop 0
	v_cndmask_b32_e64 v7, 0, v204, vcc
	v_cmp_lt_u32_e32 vcc, v145, v5
	s_nop 1
	v_cndmask_b32_e64 v8, v205, 0, vcc
	v_cmp_lt_u32_e32 vcc, v144, v5
	v_or_b32_e32 v7, v8, v7
	s_nop 0
	v_cndmask_b32_e64 v8, v206, 0, vcc
	v_cmp_lt_u32_e32 vcc, v143, v5
	s_nop 1
	v_cndmask_b32_e64 v9, v207, 0, vcc
	v_or3_b32 v7, v7, v8, v9
	v_cmp_ne_u32_e32 vcc, 0, v7
	s_and_saveexec_b64 s[0:1], vcc
	ds_or_b32 v203, v7 offset:96
	s_or_b64 exec, exec, s[0:1]
	v_xor_b32_e32 v8, v3, v144
	v_xor_b32_e32 v7, v3, v143
	v_xor_b32_e32 v10, v3, v146
	v_xor_b32_e32 v9, v3, v145
	v_min_u32_e32 v11, v8, v7
	v_min3_u32 v11, v10, v9, v11
	v_cmp_gt_u32_e32 vcc, s27, v11
	s_and_b64 s[8:9], s[40:41], vcc
	s_and_saveexec_b64 s[0:1], s[8:9]
	s_cbranch_execz .LBB0_2650
	v_cmp_gt_u32_e32 vcc, s27, v10
	s_and_saveexec_b64 s[8:9], vcc
	s_cbranch_execz .LBB0_2641
	ds_add_rtn_u32 v10, v2, v186
	s_waitcnt lgkmcnt(0)
	v_cmp_gt_u32_e32 vcc, 64, v10
	s_and_b64 exec, exec, vcc
	v_lshlrev_b32_e32 v11, 12, v146
	s_mov_b32 s7, 0x3ff000
	v_lshl_add_u32 v10, v10, 2, v40
	v_and_or_b32 v11, v11, s7, v6
	ds_write_b32 v10, v11

.LBB0_2652:
	v_cmp_ge_u32_e32 vcc, v138, v5
	v_add_u32_e32 v6, 0x400, v41
	s_nop 0
	v_cndmask_b32_e64 v7, 0, v204, vcc
	v_cmp_lt_u32_e32 vcc, v137, v5
	s_nop 1
	v_cndmask_b32_e64 v8, v205, 0, vcc
	v_cmp_lt_u32_e32 vcc, v136, v5
	v_or_b32_e32 v7, v8, v7
	s_nop 0
	v_cndmask_b32_e64 v8, v206, 0, vcc
	v_cmp_lt_u32_e32 vcc, v135, v5
	s_nop 1
	v_cndmask_b32_e64 v9, v207, 0, vcc
	v_or3_b32 v7, v7, v8, v9
	v_cmp_ne_u32_e32 vcc, 0, v7
	s_and_saveexec_b64 s[0:1], vcc
	ds_or_b32 v203, v7 offset:128
	s_or_b64 exec, exec, s[0:1]
	v_xor_b32_e32 v8, v3, v136
	v_xor_b32_e32 v7, v3, v135
	v_xor_b32_e32 v10, v3, v138
	v_xor_b32_e32 v9, v3, v137
	v_min_u32_e32 v11, v8, v7
	v_min3_u32 v11, v10, v9, v11
	v_cmp_gt_u32_e32 vcc, s27, v11
	s_and_b64 s[8:9], s[40:41], vcc
	s_and_saveexec_b64 s[0:1], s[8:9]
	s_cbranch_execz .LBB0_2667
	v_cmp_gt_u32_e32 vcc, s27, v10
	s_and_saveexec_b64 s[8:9], vcc
	s_cbranch_execz .LBB0_2658
	ds_add_rtn_u32 v10, v2, v186
	s_waitcnt lgkmcnt(0)
	v_cmp_gt_u32_e32 vcc, 64, v10
	s_and_b64 exec, exec, vcc
	v_lshlrev_b32_e32 v11, 12, v138
	s_mov_b32 s7, 0x3ff000
	v_lshl_add_u32 v10, v10, 2, v40
	v_and_or_b32 v11, v11, s7, v6
	ds_write_b32 v10, v11

.LBB0_2669:
	v_cmp_ge_u32_e32 vcc, v130, v5
	v_add_u32_e32 v6, 0x500, v41
	s_nop 0
	v_cndmask_b32_e64 v7, 0, v204, vcc
	v_cmp_lt_u32_e32 vcc, v129, v5
	s_nop 1
	v_cndmask_b32_e64 v8, v205, 0, vcc
	v_cmp_lt_u32_e32 vcc, v128, v5
	v_or_b32_e32 v7, v8, v7
	s_nop 0
	v_cndmask_b32_e64 v8, v206, 0, vcc
	v_cmp_lt_u32_e32 vcc, v127, v5
	s_nop 1
	v_cndmask_b32_e64 v9, v207, 0, vcc
	v_or3_b32 v7, v7, v8, v9
	v_cmp_ne_u32_e32 vcc, 0, v7
	s_and_saveexec_b64 s[0:1], vcc
	ds_or_b32 v203, v7 offset:160
	s_or_b64 exec, exec, s[0:1]
	v_xor_b32_e32 v8, v3, v128
	v_xor_b32_e32 v7, v3, v127
	v_xor_b32_e32 v10, v3, v130
	v_xor_b32_e32 v9, v3, v129
	v_min_u32_e32 v11, v8, v7
	v_min3_u32 v11, v10, v9, v11
	v_cmp_gt_u32_e32 vcc, s27, v11
	s_and_b64 s[8:9], s[40:41], vcc
	s_and_saveexec_b64 s[0:1], s[8:9]
	s_cbranch_execz .LBB0_2684
	v_cmp_gt_u32_e32 vcc, s27, v10
	s_and_saveexec_b64 s[8:9], vcc
	s_cbranch_execz .LBB0_2675
	ds_add_rtn_u32 v10, v2, v186
	s_waitcnt lgkmcnt(0)
	v_cmp_gt_u32_e32 vcc, 64, v10
	s_and_b64 exec, exec, vcc
	v_lshlrev_b32_e32 v11, 12, v130
	s_mov_b32 s7, 0x3ff000
	v_lshl_add_u32 v10, v10, 2, v40
	v_and_or_b32 v11, v11, s7, v6
	ds_write_b32 v10, v11

.LBB0_2686:
	v_cmp_ge_u32_e32 vcc, v122, v5
	v_add_u32_e32 v6, 0x600, v41
	s_nop 0
	v_cndmask_b32_e64 v7, 0, v204, vcc
	v_cmp_lt_u32_e32 vcc, v121, v5
	s_nop 1
	v_cndmask_b32_e64 v8, v205, 0, vcc
	v_cmp_lt_u32_e32 vcc, v120, v5
	v_or_b32_e32 v7, v8, v7
	s_nop 0
	v_cndmask_b32_e64 v8, v206, 0, vcc
	v_cmp_lt_u32_e32 vcc, v119, v5
	s_nop 1
	v_cndmask_b32_e64 v9, v207, 0, vcc
	v_or3_b32 v7, v7, v8, v9
	v_cmp_ne_u32_e32 vcc, 0, v7
	s_and_saveexec_b64 s[0:1], vcc
	ds_or_b32 v203, v7 offset:192
	s_or_b64 exec, exec, s[0:1]
	v_xor_b32_e32 v8, v3, v120
	v_xor_b32_e32 v7, v3, v119
	v_xor_b32_e32 v10, v3, v122
	v_xor_b32_e32 v9, v3, v121
	v_min_u32_e32 v11, v8, v7
	v_min3_u32 v11, v10, v9, v11
	v_cmp_gt_u32_e32 vcc, s27, v11
	s_and_b64 s[8:9], s[40:41], vcc
	s_and_saveexec_b64 s[0:1], s[8:9]
	s_cbranch_execz .LBB0_2701
	v_cmp_gt_u32_e32 vcc, s27, v10
	s_and_saveexec_b64 s[8:9], vcc
	s_cbranch_execz .LBB0_2692
	ds_add_rtn_u32 v10, v2, v186
	s_waitcnt lgkmcnt(0)
	v_cmp_gt_u32_e32 vcc, 64, v10
	s_and_b64 exec, exec, vcc
	v_lshlrev_b32_e32 v11, 12, v122
	s_mov_b32 s7, 0x3ff000
	v_lshl_add_u32 v10, v10, 2, v40
	v_and_or_b32 v11, v11, s7, v6
	ds_write_b32 v10, v11

.LBB0_2703:
	v_cmp_ge_u32_e32 vcc, v113, v5
	v_add_u32_e32 v6, 0x700, v41
	s_nop 0
	v_cndmask_b32_e64 v7, 0, v204, vcc
	v_cmp_lt_u32_e32 vcc, v112, v5
	s_nop 1
	v_cndmask_b32_e64 v8, v205, 0, vcc
	v_cmp_lt_u32_e32 vcc, v111, v5
	v_or_b32_e32 v7, v8, v7
	s_nop 0
	v_cndmask_b32_e64 v8, v206, 0, vcc
	v_cmp_lt_u32_e32 vcc, v110, v5
	s_nop 1
	v_cndmask_b32_e64 v9, v207, 0, vcc
	v_or3_b32 v7, v7, v8, v9
	v_cmp_ne_u32_e32 vcc, 0, v7
	s_and_saveexec_b64 s[0:1], vcc
	ds_or_b32 v203, v7 offset:224
	s_or_b64 exec, exec, s[0:1]
	v_xor_b32_e32 v8, v3, v111
	v_xor_b32_e32 v7, v3, v110
	v_xor_b32_e32 v10, v3, v113
	v_xor_b32_e32 v9, v3, v112
	v_min_u32_e32 v11, v8, v7
	v_min3_u32 v11, v10, v9, v11
	v_cmp_gt_u32_e32 vcc, s27, v11
	s_and_b64 s[8:9], s[40:41], vcc
	s_and_saveexec_b64 s[0:1], s[8:9]
	s_cbranch_execz .LBB0_2718
	v_cmp_gt_u32_e32 vcc, s27, v10
	s_and_saveexec_b64 s[8:9], vcc
	s_cbranch_execz .LBB0_2709
	ds_add_rtn_u32 v10, v2, v186
	s_waitcnt lgkmcnt(0)
	v_cmp_gt_u32_e32 vcc, 64, v10
	s_and_b64 exec, exec, vcc
	v_lshlrev_b32_e32 v11, 12, v113
	s_mov_b32 s7, 0x3ff000
	v_lshl_add_u32 v10, v10, 2, v40
	v_and_or_b32 v11, v11, s7, v6
	ds_write_b32 v10, v11

.LBB0_2720:
	v_cmp_ge_u32_e32 vcc, v106, v5
	v_add_u32_e32 v6, 0x800, v41
	s_nop 0
	v_cndmask_b32_e64 v7, 0, v204, vcc
	v_cmp_lt_u32_e32 vcc, v104, v5
	s_nop 1
	v_cndmask_b32_e64 v8, v205, 0, vcc
	v_cmp_lt_u32_e32 vcc, v103, v5
	v_or_b32_e32 v7, v8, v7
	s_nop 0
	v_cndmask_b32_e64 v8, v206, 0, vcc
	v_cmp_lt_u32_e32 vcc, v102, v5
	s_nop 1
	v_cndmask_b32_e64 v9, v207, 0, vcc
	v_or3_b32 v7, v7, v8, v9
	v_cmp_ne_u32_e32 vcc, 0, v7
	s_and_saveexec_b64 s[0:1], vcc
	ds_or_b32 v203, v7 offset:256
	s_or_b64 exec, exec, s[0:1]
	v_xor_b32_e32 v8, v3, v103
	v_xor_b32_e32 v7, v3, v102
	v_xor_b32_e32 v10, v3, v106
	v_xor_b32_e32 v9, v3, v104
	v_min_u32_e32 v11, v8, v7
	v_min3_u32 v11, v10, v9, v11
	v_cmp_gt_u32_e32 vcc, s27, v11
	s_and_b64 s[8:9], s[40:41], vcc
	s_and_saveexec_b64 s[0:1], s[8:9]
	s_cbranch_execz .LBB0_2735
	v_cmp_gt_u32_e32 vcc, s27, v10
	s_and_saveexec_b64 s[8:9], vcc
	s_cbranch_execz .LBB0_2726
	ds_add_rtn_u32 v10, v2, v186
	s_waitcnt lgkmcnt(0)
	v_cmp_gt_u32_e32 vcc, 64, v10
	s_and_b64 exec, exec, vcc
	v_lshlrev_b32_e32 v11, 12, v106
	s_mov_b32 s7, 0x3ff000
	v_lshl_add_u32 v10, v10, 2, v40
	v_and_or_b32 v11, v11, s7, v6
	ds_write_b32 v10, v11

.LBB0_2737:
	v_cmp_ge_u32_e32 vcc, v97, v5
	v_add_u32_e32 v6, 0x900, v41
	s_nop 0
	v_cndmask_b32_e64 v7, 0, v204, vcc
	v_cmp_lt_u32_e32 vcc, v96, v5
	s_nop 1
	v_cndmask_b32_e64 v8, v205, 0, vcc
	v_cmp_lt_u32_e32 vcc, v95, v5
	v_or_b32_e32 v7, v8, v7
	s_nop 0
	v_cndmask_b32_e64 v8, v206, 0, vcc
	v_cmp_lt_u32_e32 vcc, v94, v5
	s_nop 1
	v_cndmask_b32_e64 v9, v207, 0, vcc
	v_or3_b32 v7, v7, v8, v9
	v_cmp_ne_u32_e32 vcc, 0, v7
	s_and_saveexec_b64 s[0:1], vcc
	ds_or_b32 v203, v7 offset:288
	s_or_b64 exec, exec, s[0:1]
	v_xor_b32_e32 v8, v3, v95
	v_xor_b32_e32 v7, v3, v94
	v_xor_b32_e32 v10, v3, v97
	v_xor_b32_e32 v9, v3, v96
	v_min_u32_e32 v11, v8, v7
	v_min3_u32 v11, v10, v9, v11
	v_cmp_gt_u32_e32 vcc, s27, v11
	s_and_b64 s[8:9], s[40:41], vcc
	s_and_saveexec_b64 s[0:1], s[8:9]
	s_cbranch_execz .LBB0_2752
	v_cmp_gt_u32_e32 vcc, s27, v10
	s_and_saveexec_b64 s[8:9], vcc
	s_cbranch_execz .LBB0_2743
	ds_add_rtn_u32 v10, v2, v186
	s_waitcnt lgkmcnt(0)
	v_cmp_gt_u32_e32 vcc, 64, v10
	s_and_b64 exec, exec, vcc
	v_lshlrev_b32_e32 v11, 12, v97
	s_mov_b32 s7, 0x3ff000
	v_lshl_add_u32 v10, v10, 2, v40
	v_and_or_b32 v11, v11, s7, v6
	ds_write_b32 v10, v11

.LBB0_2754:
	v_cmp_ge_u32_e32 vcc, v89, v5
	v_add_u32_e32 v6, 0xa00, v41
	s_nop 0
	v_cndmask_b32_e64 v7, 0, v204, vcc
	v_cmp_lt_u32_e32 vcc, v88, v5
	s_nop 1
	v_cndmask_b32_e64 v8, v205, 0, vcc
	v_cmp_lt_u32_e32 vcc, v87, v5
	v_or_b32_e32 v7, v8, v7
	s_nop 0
	v_cndmask_b32_e64 v8, v206, 0, vcc
	v_cmp_lt_u32_e32 vcc, v86, v5
	s_nop 1
	v_cndmask_b32_e64 v9, v207, 0, vcc
	v_or3_b32 v7, v7, v8, v9
	v_cmp_ne_u32_e32 vcc, 0, v7
	s_and_saveexec_b64 s[0:1], vcc
	ds_or_b32 v203, v7 offset:320
	s_or_b64 exec, exec, s[0:1]
	v_xor_b32_e32 v8, v3, v87
	v_xor_b32_e32 v7, v3, v86
	v_xor_b32_e32 v10, v3, v89
	v_xor_b32_e32 v9, v3, v88
	v_min_u32_e32 v11, v8, v7
	v_min3_u32 v11, v10, v9, v11
	v_cmp_gt_u32_e32 vcc, s27, v11
	s_and_b64 s[8:9], s[40:41], vcc
	s_and_saveexec_b64 s[0:1], s[8:9]
	s_cbranch_execz .LBB0_2769
	v_cmp_gt_u32_e32 vcc, s27, v10
	s_and_saveexec_b64 s[8:9], vcc
	s_cbranch_execz .LBB0_2760
	ds_add_rtn_u32 v10, v2, v186
	s_waitcnt lgkmcnt(0)
	v_cmp_gt_u32_e32 vcc, 64, v10
	s_and_b64 exec, exec, vcc
	v_lshlrev_b32_e32 v11, 12, v89
	s_mov_b32 s7, 0x3ff000
	v_lshl_add_u32 v10, v10, 2, v40
	v_and_or_b32 v11, v11, s7, v6
	ds_write_b32 v10, v11

.LBB0_2771:
	v_cmp_ge_u32_e32 vcc, v81, v5
	v_add_u32_e32 v6, 0xb00, v41
	s_nop 0
	v_cndmask_b32_e64 v7, 0, v204, vcc
	v_cmp_lt_u32_e32 vcc, v80, v5
	s_nop 1
	v_cndmask_b32_e64 v8, v205, 0, vcc
	v_cmp_lt_u32_e32 vcc, v79, v5
	v_or_b32_e32 v7, v8, v7
	s_nop 0
	v_cndmask_b32_e64 v8, v206, 0, vcc
	v_cmp_lt_u32_e32 vcc, v78, v5
	s_nop 1
	v_cndmask_b32_e64 v9, v207, 0, vcc
	v_or3_b32 v7, v7, v8, v9
	v_cmp_ne_u32_e32 vcc, 0, v7
	s_and_saveexec_b64 s[0:1], vcc
	ds_or_b32 v203, v7 offset:352
	s_or_b64 exec, exec, s[0:1]
	v_xor_b32_e32 v8, v3, v79
	v_xor_b32_e32 v7, v3, v78
	v_xor_b32_e32 v10, v3, v81
	v_xor_b32_e32 v9, v3, v80
	v_min_u32_e32 v11, v8, v7
	v_min3_u32 v11, v10, v9, v11
	v_cmp_gt_u32_e32 vcc, s27, v11
	s_and_b64 s[8:9], s[40:41], vcc
	s_and_saveexec_b64 s[0:1], s[8:9]
	s_cbranch_execz .LBB0_2786
	v_cmp_gt_u32_e32 vcc, s27, v10
	s_and_saveexec_b64 s[8:9], vcc
	s_cbranch_execz .LBB0_2777
	ds_add_rtn_u32 v10, v2, v186
	s_waitcnt lgkmcnt(0)
	v_cmp_gt_u32_e32 vcc, 64, v10
	s_and_b64 exec, exec, vcc
	v_lshlrev_b32_e32 v11, 12, v81
	s_mov_b32 s7, 0x3ff000
	v_lshl_add_u32 v10, v10, 2, v40
	v_and_or_b32 v11, v11, s7, v6
	ds_write_b32 v10, v11

.LBB0_2788:
	v_cmp_ge_u32_e32 vcc, v73, v5
	v_add_u32_e32 v6, 0xc00, v41
	s_nop 0
	v_cndmask_b32_e64 v7, 0, v204, vcc
	v_cmp_lt_u32_e32 vcc, v72, v5
	s_nop 1
	v_cndmask_b32_e64 v8, v205, 0, vcc
	v_cmp_lt_u32_e32 vcc, v71, v5
	v_or_b32_e32 v7, v8, v7
	s_nop 0
	v_cndmask_b32_e64 v8, v206, 0, vcc
	v_cmp_lt_u32_e32 vcc, v70, v5
	s_nop 1
	v_cndmask_b32_e64 v9, v207, 0, vcc
	v_or3_b32 v7, v7, v8, v9
	v_cmp_ne_u32_e32 vcc, 0, v7
	s_and_saveexec_b64 s[0:1], vcc
	ds_or_b32 v203, v7 offset:384
	s_or_b64 exec, exec, s[0:1]
	v_xor_b32_e32 v8, v3, v71
	v_xor_b32_e32 v7, v3, v70
	v_xor_b32_e32 v10, v3, v73
	v_xor_b32_e32 v9, v3, v72
	v_min_u32_e32 v11, v8, v7
	v_min3_u32 v11, v10, v9, v11
	v_cmp_gt_u32_e32 vcc, s27, v11
	s_and_b64 s[8:9], s[40:41], vcc
	s_and_saveexec_b64 s[0:1], s[8:9]
	s_cbranch_execz .LBB0_2803
	v_cmp_gt_u32_e32 vcc, s27, v10
	s_and_saveexec_b64 s[8:9], vcc
	s_cbranch_execz .LBB0_2794
	ds_add_rtn_u32 v10, v2, v186
	s_waitcnt lgkmcnt(0)
	v_cmp_gt_u32_e32 vcc, 64, v10
	s_and_b64 exec, exec, vcc
	v_lshlrev_b32_e32 v11, 12, v73
	s_mov_b32 s7, 0x3ff000
	v_lshl_add_u32 v10, v10, 2, v40
	v_and_or_b32 v11, v11, s7, v6
	ds_write_b32 v10, v11

.LBB0_2805:
	v_cmp_ge_u32_e32 vcc, v65, v5
	v_add_u32_e32 v6, 0xd00, v41
	s_nop 0
	v_cndmask_b32_e64 v7, 0, v204, vcc
	v_cmp_lt_u32_e32 vcc, v64, v5
	s_nop 1
	v_cndmask_b32_e64 v8, v205, 0, vcc
	v_cmp_lt_u32_e32 vcc, v63, v5
	v_or_b32_e32 v7, v8, v7
	s_nop 0
	v_cndmask_b32_e64 v8, v206, 0, vcc
	v_cmp_lt_u32_e32 vcc, v62, v5
	s_nop 1
	v_cndmask_b32_e64 v9, v207, 0, vcc
	v_or3_b32 v7, v7, v8, v9
	v_cmp_ne_u32_e32 vcc, 0, v7
	s_and_saveexec_b64 s[0:1], vcc
	ds_or_b32 v203, v7 offset:416
	s_or_b64 exec, exec, s[0:1]
	v_xor_b32_e32 v8, v3, v63
	v_xor_b32_e32 v7, v3, v62
	v_xor_b32_e32 v10, v3, v65
	v_xor_b32_e32 v9, v3, v64
	v_min_u32_e32 v11, v8, v7
	v_min3_u32 v11, v10, v9, v11
	v_cmp_gt_u32_e32 vcc, s27, v11
	s_and_b64 s[8:9], s[40:41], vcc
	s_and_saveexec_b64 s[0:1], s[8:9]
	s_cbranch_execz .LBB0_2820
	v_cmp_gt_u32_e32 vcc, s27, v10
	s_and_saveexec_b64 s[8:9], vcc
	s_cbranch_execz .LBB0_2811
	ds_add_rtn_u32 v10, v2, v186
	s_waitcnt lgkmcnt(0)
	v_cmp_gt_u32_e32 vcc, 64, v10
	s_and_b64 exec, exec, vcc
	v_lshlrev_b32_e32 v11, 12, v65
	s_mov_b32 s7, 0x3ff000
	v_lshl_add_u32 v10, v10, 2, v40
	v_and_or_b32 v11, v11, s7, v6
	ds_write_b32 v10, v11

.LBB0_2822:
	v_cmp_ge_u32_e32 vcc, v57, v5
	v_add_u32_e32 v6, 0xe00, v41
	s_nop 0
	v_cndmask_b32_e64 v7, 0, v204, vcc
	v_cmp_lt_u32_e32 vcc, v56, v5
	s_nop 1
	v_cndmask_b32_e64 v8, v205, 0, vcc
	v_cmp_lt_u32_e32 vcc, v55, v5
	v_or_b32_e32 v7, v8, v7
	s_nop 0
	v_cndmask_b32_e64 v8, v206, 0, vcc
	v_cmp_lt_u32_e32 vcc, v54, v5
	s_nop 1
	v_cndmask_b32_e64 v9, v207, 0, vcc
	v_or3_b32 v7, v7, v8, v9
	v_cmp_ne_u32_e32 vcc, 0, v7
	s_and_saveexec_b64 s[0:1], vcc
	ds_or_b32 v203, v7 offset:448
	s_or_b64 exec, exec, s[0:1]
	v_xor_b32_e32 v8, v3, v55
	v_xor_b32_e32 v7, v3, v54
	v_xor_b32_e32 v10, v3, v57
	v_xor_b32_e32 v9, v3, v56
	v_min_u32_e32 v11, v8, v7
	v_min3_u32 v11, v10, v9, v11
	v_cmp_gt_u32_e32 vcc, s27, v11
	s_and_b64 s[8:9], s[40:41], vcc
	s_and_saveexec_b64 s[0:1], s[8:9]
	s_cbranch_execz .LBB0_2837
	v_cmp_gt_u32_e32 vcc, s27, v10
	s_and_saveexec_b64 s[8:9], vcc
	s_cbranch_execz .LBB0_2828
	ds_add_rtn_u32 v10, v2, v186
	s_waitcnt lgkmcnt(0)
	v_cmp_gt_u32_e32 vcc, 64, v10
	s_and_b64 exec, exec, vcc
	v_lshlrev_b32_e32 v11, 12, v57
	s_mov_b32 s7, 0x3ff000
	v_lshl_add_u32 v10, v10, 2, v40
	v_and_or_b32 v11, v11, s7, v6
	ds_write_b32 v10, v11

.LBB0_2839:
	v_cmp_ge_u32_e32 vcc, v49, v5
	v_add_u32_e32 v6, 0xf00, v41
	s_nop 0
	v_cndmask_b32_e64 v7, 0, v204, vcc
	v_cmp_lt_u32_e32 vcc, v48, v5
	s_nop 1
	v_cndmask_b32_e64 v8, v205, 0, vcc
	v_cmp_lt_u32_e32 vcc, v47, v5
	v_or_b32_e32 v7, v8, v7
	s_nop 0
	v_cndmask_b32_e64 v8, v206, 0, vcc
	v_cmp_lt_u32_e32 vcc, v46, v5
	s_nop 1
	v_cndmask_b32_e64 v9, v207, 0, vcc
	v_or3_b32 v7, v7, v8, v9
	v_cmp_ne_u32_e32 vcc, 0, v7
	s_and_saveexec_b64 s[0:1], vcc
	ds_or_b32 v203, v7 offset:480
	s_or_b64 exec, exec, s[0:1]
	v_xor_b32_e32 v8, v3, v47
	v_xor_b32_e32 v7, v3, v46
	v_xor_b32_e32 v10, v3, v49
	v_xor_b32_e32 v9, v3, v48
	v_min_u32_e32 v11, v8, v7
	v_min3_u32 v11, v10, v9, v11
	v_cmp_gt_u32_e32 vcc, s27, v11
	s_and_b64 s[8:9], s[40:41], vcc
	s_and_saveexec_b64 s[0:1], s[8:9]
	s_cbranch_execz .LBB0_2854
	v_cmp_gt_u32_e32 vcc, s27, v10
	s_and_saveexec_b64 s[8:9], vcc
	s_cbranch_execz .LBB0_2845
	ds_add_rtn_u32 v10, v2, v186
	s_waitcnt lgkmcnt(0)
	v_cmp_gt_u32_e32 vcc, 64, v10
	s_and_b64 exec, exec, vcc
	v_lshlrev_b32_e32 v11, 12, v49
	s_mov_b32 s7, 0x3ff000
	v_lshl_add_u32 v10, v10, 2, v40
	v_and_or_b32 v11, v11, s7, v6
	ds_write_b32 v10, v11
